# plus attention loop: the first four exps of a tile issued behind the first K-fragment reads, in front of the first LDS wait
# baseline (speedup 1.0000x reference)
.LBB0_961:
	s_waitcnt vmcnt(5)
	s_barrier
	s_mov_b32 s19, s5
	s_mov_b32 s5, s25
	s_mul_i32 s9, s25, 0x6000
	s_add_i32 s25, s9, 0
	v_add_u32_e32 v124, s25, v225
	ds_read_b128 v[120:123], v124
	ds_read_b128 v[160:163], v124 offset:4096
	ds_read_b128 v[168:171], v124 offset:8192
	ds_read_b128 v[172:175], v124 offset:12288
	v_exp_f32_e32 v188, v148
	v_exp_f32_e32 v189, v149
	v_exp_f32_e32 v194, v150
	v_exp_f32_e32 v195, v151
	s_waitcnt lgkmcnt(3)
	v_mfma_f32_16x16x32_bf16 v[124:127], v[120:123], v[4:7], v[48:51]
	v_mfma_f32_16x16x32_bf16 v[120:123], v[120:123], v[40:43], v[52:55]
	v_add_u32_e32 v196, s25, v234
	ds_read_b128 v[184:187], v196
	s_waitcnt lgkmcnt(3)
	v_mfma_f32_16x16x32_bf16 v[148:151], v[160:163], v[4:7], v[48:51]
	v_add_f32_e32 v180, v157, v156
	v_add_f32_e32 v181, v145, v144
	v_mfma_f32_16x16x32_bf16 v[160:163], v[160:163], v[40:43], v[52:55]
	ds_read_b128 v[176:179], v196 offset:4096
	s_waitcnt lgkmcnt(3)
	v_mfma_f32_16x16x32_bf16 v[164:167], v[168:171], v[4:7], v[48:51]
	v_exp_f32_e32 v190, v140
	v_exp_f32_e32 v191, v141
	v_add_f32_e32 v206, v158, v180
	v_mfma_f32_16x16x32_bf16 v[168:171], v[168:171], v[40:43], v[52:55]
	v_add_f32_e32 v207, v146, v181
	ds_read_b128 v[180:183], v196 offset:8192
	v_exp_f32_e32 v192, v142
	v_exp_f32_e32 v193, v143
	s_waitcnt lgkmcnt(3)
	v_mfma_f32_16x16x32_bf16 v[140:143], v[172:175], v[4:7], v[48:51]
	v_add_f32_e32 v206, v159, v206
	v_add_f32_e32 v207, v147, v207
	v_mfma_f32_16x16x32_bf16 v[172:175], v[172:175], v[40:43], v[52:55]
	s_add_i32 s9, s4, -1
	s_cmp_ge_u32 s9, s2
	s_cbranch_scc1 .LBB0_963
	s_add_u32 s9, s6, s30
	s_addc_u32 s35, s7, s31
	s_add_u32 s34, s9, 0x180000
	s_addc_u32 s35, s35, 0
	s_add_u32 s36, s10, 0xffffe000
	s_mul_i32 s9, s8, 0x6000
	s_addc_u32 s37, s11, -1
	s_add_i32 s9, s9, 0
	s_add_i32 s48, s9, s77
	s_mov_b32 m0, s48
	s_add_i32 s9, s9, s97
	global_load_lds_dwordx4 v227, s[34:35]
	s_add_i32 m0, s48, 0x400
	s_nop 0
	global_load_lds_dwordx4 v229, s[34:35]
	s_add_i32 m0, s9, 0x4000
	s_nop 0
	global_load_lds_dwordx4 v232, s[36:37]

.LBB0_969:
	s_waitcnt vmcnt(5)
	s_barrier
	s_mul_i32 s34, s19, 0x6000
	s_add_i32 s49, s34, 0
	v_add_u32_e32 v164, s49, v225
	ds_read_b128 v[160:163], v164
	ds_read_b128 v[168:171], v164 offset:4096
	ds_read_b128 v[184:187], v164 offset:8192
	ds_read_b128 v[246:249], v164 offset:12288
	v_exp_f32_e32 v235, v140
	v_exp_f32_e32 v236, v141
	v_exp_f32_e32 v241, v142
	v_exp_f32_e32 v242, v143
	s_waitcnt lgkmcnt(3)
	v_mfma_f32_16x16x32_bf16 v[164:167], v[160:163], v[4:7], v[120:123]
	v_mfma_f32_16x16x32_bf16 v[160:163], v[160:163], v[40:43], v[124:127]
	v_add_u32_e32 v243, s49, v234
	ds_read_b128 v[192:195], v243
	s_waitcnt lgkmcnt(3)
	v_mfma_f32_16x16x32_bf16 v[180:183], v[168:171], v[4:7], v[120:123]
	v_add_f32_e32 v140, v153, v152
	v_mfma_f32_16x16x32_bf16 v[172:175], v[168:171], v[40:43], v[124:127]
	v_add_f32_e32 v141, v145, v144
	ds_read_b128 v[188:191], v243 offset:4096
	v_exp_f32_e32 v237, v136
	v_exp_f32_e32 v238, v137
	s_waitcnt lgkmcnt(3)
	v_mfma_f32_16x16x32_bf16 v[176:179], v[184:187], v[4:7], v[120:123]
	v_add_f32_e32 v136, v154, v140
	v_add_f32_e32 v137, v146, v141
	v_mfma_f32_16x16x32_bf16 v[140:143], v[184:187], v[40:43], v[124:127]
	ds_read_b128 v[184:187], v243 offset:8192
	v_exp_f32_e32 v239, v138
	v_exp_f32_e32 v240, v139
	s_waitcnt lgkmcnt(3)
	v_mfma_f32_16x16x32_bf16 v[168:171], v[246:249], v[4:7], v[120:123]
	v_add_f32_e32 v245, v155, v136
	v_add_f32_e32 v244, v147, v137
	v_mfma_f32_16x16x32_bf16 v[136:139], v[246:249], v[40:43], v[124:127]
	s_cmp_ge_u32 s4, s2
	s_cselect_b64 s[34:35], -1, 0
	s_and_b64 vcc, exec, s[34:35]
	s_cbranch_vccnz .LBB0_971
	s_add_u32 s65, s6, s30
	s_addc_u32 s69, s7, s31
	s_add_u32 s70, s65, 0x200000
	s_addc_u32 s71, s69, 0
	s_add_i32 s65, s25, s77
	s_mov_b64 s[80:81], s[10:11]
	s_mov_b32 m0, s65
	s_add_i32 s25, s25, s97
	global_load_lds_dwordx4 v227, s[70:71]
	s_add_i32 m0, s65, 0x400
	s_nop 0
	global_load_lds_dwordx4 v229, s[70:71]
	s_add_i32 m0, s25, 0x4000
	s_nop 0
	global_load_lds_dwordx4 v232, s[80:81]
